# weight convert split: layer-3-only weights converted by the 192 workgroups idle during SCAN_C instead of in the first phase; convert tile code hand-written (same 64x64 LDS transpose)
# speedup vs baseline: 1.0043x; 1.0043x over previous
; #define MFMA32(a, b, c) __builtin_amdgcn_mfma_f32_32x32x16_bf16((a), (b), (c), 0, 0, 0)
; DI void phase_scan_c(int wv_, int vb_, int nvb_, char* ws_, const Ctx& p, char* smem, int half) {
;     ...
;       const size_t uix = (size_t)blk * 32 + nc;
;       const float egl = GL[uix];
;       bf16x8 ucur[4];
; #pragma unroll
;       for (int tb = 0; tb < 2; ++tb) { ucur[2 * tb] = *(const bf16x8*)(CU + (uix * 128 + dv0 + c) * 64 + h * 16 + tb * 32); ucur[2 * tb + 1] = *(const bf16x8*)(CU + (uix * 128 + dv0 + c) * 64 + h * 16 + tb * 32 + 8); }
;       const u16* Wp = sW + c * 136 + h * 8;
;       const u16* Qp = sQ + c * 136 + h * 8;
;       const u16* KTp = sKT + c * 72 + h * 8;
;       const u16* QKp = sQK + c * 72 + h * 8;
;       f32x16 X[2], Oa[2];
;       X[0] = zero16(); X[1] = zero16(); Oa[0] = zero16(); Oa[1] = zero16();
; #pragma unroll
;       for (int mb = 0; mb < 4; ++mb) {
; #pragma unroll
;         for (int s = 0; s < 2; ++s) {
;           const bf16x8 sb = pack8(S[mb], s);
; #pragma unroll
;           for (int tb = 0; tb < 2; ++tb) {
;             bf16x8 a = *(const bf16x8*)(Wp + tb * 32 * 136 + mb * 32 + s * 16);
;             bf16x8 a2 = *(const bf16x8*)(Qp + tb * 32 * 136 + mb * 32 + s * 16);
;             X[tb] = MFMA32(a, sb, X[tb]);
;             Oa[tb] = MFMA32(a2, sb, Oa[tb]);
;           }
;         }
;       }
;     ...
;       for (int mb = 0; mb < 4; ++mb) {
; #pragma unroll
;         for (int i = 0; i < 16; ++i) S[mb][i] *= egl;
.LBB0_232:
	s_add_u32 s12, s4, s16
	s_addc_u32 s13, s5, s17
	v_lshl_add_u64 v[2:3], v[186:187], 0, s[16:17]
	global_load_dword v0, v1, s[12:13]
	global_load_dwordx4 v[144:147], v[2:3], off offset:-64
	global_load_dwordx4 v[10:13], v[2:3], off offset:-48
	global_load_dwordx4 v[6:9], v[2:3], off
	s_nop 0
	global_load_dwordx4 v[2:5], v[2:3], off offset:16
	ds_read_b128 v[84:87], v216 offset:17408
	ds_read_b128 v[88:91], v216
	ds_read_b128 v[148:151], v216 offset:32
	v_cvt_pk_bf16_f32 v80, v16, v17
	v_cvt_pk_bf16_f32 v81, v18, v19
	v_cvt_pk_bf16_f32 v82, v20, v21
	v_cvt_pk_bf16_f32 v83, v22, v23
	v_cvt_pk_bf16_f32 v152, v24, v25
	v_cvt_pk_bf16_f32 v153, v26, v27
	s_waitcnt lgkmcnt(1)
	v_mfma_f32_32x32x16_bf16 v[128:143], v[88:91], v[80:83], 0
	v_cvt_pk_bf16_f32 v154, v28, v29
	v_cvt_pk_bf16_f32 v155, v30, v31
	v_add_co_u32_e64 v218, s[12:13], s1, 1
	s_add_i32 s1, s1, 33
	s_and_b64 s[12:13], s[12:13], exec
	s_cselect_b32 s1, 31, s1
	v_mfma_f32_32x32x16_bf16 v[96:111], v[84:87], v[80:83], 0
	ds_read_b128 v[84:87], v216 offset:8704
	ds_read_b128 v[88:91], v216 offset:26112
	ds_read_b128 v[156:159], v216 offset:17440
	s_add_u32 s12, s56, s1
	s_addc_u32 s13, s57, 0
	s_lshl_b64 s[18:19], s[12:13], 13
	s_lshl_b64 s[12:13], s[12:13], 14
	s_add_u32 s34, s6, s12
	s_waitcnt lgkmcnt(2)
	v_mfma_f32_32x32x16_bf16 v[112:127], v[84:87], v[80:83], 0
	s_addc_u32 s35, s7, s13
	s_add_u32 s44, s8, s12
	s_addc_u32 s45, s9, s13
	s_add_u32 s12, s10, s12
	s_addc_u32 s13, s11, s13
	v_lshl_add_u64 v[160:161], s[12:13], 0, v[200:201]
	v_readfirstlane_b32 s0, v218
	s_waitcnt lgkmcnt(1)
	v_mfma_f32_32x32x16_bf16 v[80:95], v[88:91], v[80:83], 0
	v_lshl_add_u64 v[186:187], v[186:187], 0, s[2:3]
	s_mov_b32 s1, s0
	s_waitcnt vmcnt(4)
	v_mul_f32_e64 v30, v30, v0
	v_mul_f32_e64 v31, v31, v0
	v_mfma_f32_32x32x16_bf16 v[128:143], v[148:151], v[152:155], v[128:143]
	v_mul_f32_e64 v28, v28, v0
	v_mul_f32_e64 v29, v29, v0
	v_mul_f32_e64 v26, v26, v0
	v_mul_f32_e64 v27, v27, v0
	v_mul_f32_e64 v24, v24, v0
	v_mul_f32_e64 v25, v25, v0
	v_pk_mul_f32 v[22:23], v[22:23], v[0:1] op_sel_hi:[1,0]
	v_pk_mul_f32 v[20:21], v[20:21], v[0:1] op_sel_hi:[1,0]
	v_pk_mul_f32 v[18:19], v[18:19], v[0:1] op_sel_hi:[1,0]
	v_pk_mul_f32 v[16:17], v[16:17], v[0:1] op_sel_hi:[1,0]
	s_waitcnt lgkmcnt(0)
	v_mfma_f32_32x32x16_bf16 v[96:111], v[156:159], v[152:155], v[96:111]
	ds_read_b128 v[148:151], v216 offset:8736
	ds_read_b128 v[156:159], v216 offset:26144
	s_waitcnt lgkmcnt(1)
	v_mfma_f32_32x32x16_bf16 v[112:127], v[148:151], v[152:155], v[112:127]
	v_cvt_pk_bf16_f32 v148, v32, v33
	v_cvt_pk_bf16_f32 v149, v34, v35
	v_cvt_pk_bf16_f32 v150, v36, v37
	v_cvt_pk_bf16_f32 v151, v38, v39
	v_mul_f32_e64 v38, v38, v0
	v_mul_f32_e64 v39, v39, v0
	v_pk_mul_f32 v[36:37], v[36:37], v[0:1] op_sel_hi:[1,0]
	v_pk_mul_f32 v[34:35], v[34:35], v[0:1] op_sel_hi:[1,0]
	s_waitcnt lgkmcnt(0)
	v_mfma_f32_32x32x16_bf16 v[80:95], v[156:159], v[152:155], v[80:95]
	ds_read_b128 v[152:155], v216 offset:64
	ds_read_b128 v[156:159], v216 offset:17472
	v_mul_f32_e64 v32, v32, v0
	v_mul_f32_e64 v33, v33, v0
	s_waitcnt lgkmcnt(1)
	v_mfma_f32_32x32x16_bf16 v[128:143], v[152:155], v[148:151], v[128:143]
	s_waitcnt lgkmcnt(0)
	v_mfma_f32_32x32x16_bf16 v[96:111], v[156:159], v[148:151], v[96:111]
	ds_read_b128 v[152:155], v216 offset:8768
	ds_read_b128 v[156:159], v216 offset:26176
	s_waitcnt lgkmcnt(1)
	v_mfma_f32_32x32x16_bf16 v[112:127], v[152:155], v[148:151], v[112:127]
	s_waitcnt lgkmcnt(0)
	v_mfma_f32_32x32x16_bf16 v[80:95], v[156:159], v[148:151], v[80:95]
	ds_read_b128 v[152:155], v216 offset:96
	ds_read_b128 v[156:159], v216 offset:17504
	v_cvt_pk_bf16_f32 v148, v40, v41
	v_cvt_pk_bf16_f32 v149, v42, v43
	v_cvt_pk_bf16_f32 v150, v44, v45
	v_cvt_pk_bf16_f32 v151, v46, v47
	v_pk_mul_f32 v[46:47], v[46:47], v[0:1] op_sel_hi:[1,0]
	v_pk_mul_f32 v[44:45], v[44:45], v[0:1] op_sel_hi:[1,0]
	s_waitcnt lgkmcnt(1)
	v_mfma_f32_32x32x16_bf16 v[128:143], v[152:155], v[148:151], v[128:143]
	v_mul_f32_e64 v42, v42, v0
	v_mul_f32_e64 v43, v43, v0
	v_mul_f32_e64 v40, v40, v0
	v_mul_f32_e64 v41, v41, v0
	s_waitcnt lgkmcnt(0)
	v_mfma_f32_32x32x16_bf16 v[96:111], v[156:159], v[148:151], v[96:111]
	ds_read_b128 v[152:155], v216 offset:8800
	ds_read_b128 v[156:159], v216 offset:26208
	s_waitcnt lgkmcnt(1)
	v_mfma_f32_32x32x16_bf16 v[112:127], v[152:155], v[148:151], v[112:127]
	s_waitcnt lgkmcnt(0)
	v_mfma_f32_32x32x16_bf16 v[80:95], v[156:159], v[148:151], v[80:95]
	ds_read_b128 v[152:155], v216 offset:128
	ds_read_b128 v[156:159], v216 offset:17536
	v_cvt_pk_bf16_f32 v148, v48, v49
	v_cvt_pk_bf16_f32 v149, v50, v51
	v_cvt_pk_bf16_f32 v150, v52, v53
	v_cvt_pk_bf16_f32 v151, v54, v55
	v_pk_mul_f32 v[54:55], v[54:55], v[0:1] op_sel_hi:[1,0]
	v_pk_mul_f32 v[52:53], v[52:53], v[0:1] op_sel_hi:[1,0]
	s_waitcnt lgkmcnt(1)
	v_mfma_f32_32x32x16_bf16 v[128:143], v[152:155], v[148:151], v[128:143]
	v_mul_f32_e64 v50, v50, v0
	v_mul_f32_e64 v51, v51, v0
	v_mul_f32_e64 v48, v48, v0
	v_mul_f32_e64 v49, v49, v0
	s_waitcnt lgkmcnt(0)
	v_mfma_f32_32x32x16_bf16 v[96:111], v[156:159], v[148:151], v[96:111]
	ds_read_b128 v[152:155], v216 offset:8832
	ds_read_b128 v[156:159], v216 offset:26240
	s_waitcnt lgkmcnt(1)
	v_mfma_f32_32x32x16_bf16 v[112:127], v[152:155], v[148:151], v[112:127]
	s_waitcnt lgkmcnt(0)
	v_mfma_f32_32x32x16_bf16 v[80:95], v[156:159], v[148:151], v[80:95]
	ds_read_b128 v[152:155], v216 offset:160
	ds_read_b128 v[156:159], v216 offset:17568
	v_cvt_pk_bf16_f32 v148, v56, v57
	v_cvt_pk_bf16_f32 v149, v58, v59
	v_cvt_pk_bf16_f32 v150, v60, v61
	v_cvt_pk_bf16_f32 v151, v62, v63
	v_pk_mul_f32 v[62:63], v[62:63], v[0:1] op_sel_hi:[1,0]
	v_pk_mul_f32 v[60:61], v[60:61], v[0:1] op_sel_hi:[1,0]
	s_waitcnt lgkmcnt(1)
; #define MFMA32(a, b, c) __builtin_amdgcn_mfma_f32_32x32x16_bf16((a), (b), (c), 0, 0, 0)
; DI float bfs(short v) { return __uint_as_float(((unsigned)(u16)v) << 16); }
; DI void phase_scan_c(int wv_, int vb_, int nvb_, char* ws_, const Ctx& p, char* smem, int half) {
;     ...
;       bf16x8 vb[2][2];
; #pragma unroll
;       for (int tb = 0; tb < 2; ++tb) {
; #pragma unroll
;         for (int i = 0; i < 8; ++i) { X[tb][i] = bfs(ucur[2 * tb][i]) - X[tb][i]; X[tb][8 + i] = bfs(ucur[2 * tb + 1][i]) - X[tb][8 + i]; }
;         vb[tb][0] = pack8(X[tb], 0); vb[tb][1] = pack8(X[tb], 1);
;       }
;       { const int ncn = nc < 31 ? nc + 1 : 31; SLOAD((size_t)blk * 32 + ncn) }
; #pragma unroll
;       for (int tb = 0; tb < 2; ++tb)
; #pragma unroll
;         for (int tb2 = 0; tb2 < 2; ++tb2)
; #pragma unroll
;           for (int s = 0; s < 2; ++s) {
;             bf16x8 a = *(const bf16x8*)(QKp + tb * 32 * 72 + tb2 * 32 + s * 16);
;             Oa[tb] = MFMA32(a, vb[tb2][s], Oa[tb]);
;           }
	v_mfma_f32_32x32x16_bf16 v[128:143], v[152:155], v[148:151], v[128:143]
	v_mul_f32_e64 v58, v58, v0
	v_mul_f32_e64 v59, v59, v0
	v_mul_f32_e64 v56, v56, v0
	v_mul_f32_e64 v57, v57, v0
	s_waitcnt lgkmcnt(0)
	v_mfma_f32_32x32x16_bf16 v[96:111], v[156:159], v[148:151], v[96:111]
	ds_read_b128 v[152:155], v216 offset:8864
	ds_read_b128 v[156:159], v216 offset:26272
	s_waitcnt lgkmcnt(1)
	v_mfma_f32_32x32x16_bf16 v[112:127], v[152:155], v[148:151], v[112:127]
	s_waitcnt lgkmcnt(0)
	v_mfma_f32_32x32x16_bf16 v[80:95], v[156:159], v[148:151], v[80:95]
	ds_read_b128 v[152:155], v216 offset:192
	ds_read_b128 v[156:159], v216 offset:17600
	v_cvt_pk_bf16_f32 v148, v64, v65
	v_cvt_pk_bf16_f32 v149, v66, v67
	v_cvt_pk_bf16_f32 v150, v68, v69
	v_cvt_pk_bf16_f32 v151, v70, v71
	v_pk_mul_f32 v[70:71], v[70:71], v[0:1] op_sel_hi:[1,0]
	v_pk_mul_f32 v[68:69], v[68:69], v[0:1] op_sel_hi:[1,0]
	s_waitcnt lgkmcnt(1)
	v_mfma_f32_32x32x16_bf16 v[128:143], v[152:155], v[148:151], v[128:143]
	v_mul_f32_e64 v66, v66, v0
	v_mul_f32_e64 v67, v67, v0
	v_mul_f32_e64 v64, v64, v0
	v_mul_f32_e64 v65, v65, v0
	s_waitcnt lgkmcnt(0)
	v_mfma_f32_32x32x16_bf16 v[96:111], v[156:159], v[148:151], v[96:111]
	ds_read_b128 v[152:155], v216 offset:8896
	ds_read_b128 v[156:159], v216 offset:26304
	s_waitcnt lgkmcnt(1)
	v_mfma_f32_32x32x16_bf16 v[112:127], v[152:155], v[148:151], v[112:127]
	s_waitcnt lgkmcnt(0)
	v_mfma_f32_32x32x16_bf16 v[80:95], v[156:159], v[148:151], v[80:95]
	ds_read_b128 v[152:155], v216 offset:224
	ds_read_b128 v[156:159], v216 offset:17632
	v_cvt_pk_bf16_f32 v148, v72, v73
	v_cvt_pk_bf16_f32 v149, v74, v75
	v_cvt_pk_bf16_f32 v150, v76, v77
	v_cvt_pk_bf16_f32 v151, v78, v79
	v_pk_mul_f32 v[78:79], v[78:79], v[0:1] op_sel_hi:[1,0]
	v_pk_mul_f32 v[76:77], v[76:77], v[0:1] op_sel_hi:[1,0]
	s_waitcnt lgkmcnt(1)
	v_mfma_f32_32x32x16_bf16 v[128:143], v[152:155], v[148:151], v[128:143]
	v_mul_f32_e64 v74, v74, v0
	v_mul_f32_e64 v75, v75, v0
	v_mul_f32_e64 v72, v72, v0
	v_mul_f32_e64 v73, v73, v0
	s_waitcnt lgkmcnt(0)
	v_mfma_f32_32x32x16_bf16 v[96:111], v[156:159], v[148:151], v[96:111]
	ds_read_b128 v[152:155], v216 offset:8928
	ds_read_b128 v[156:159], v216 offset:26336
	ds_read_b128 v[220:223], v217 offset:53248
	global_load_dwordx4 v[160:163], v[160:161], off
	s_waitcnt lgkmcnt(2)
	v_mfma_f32_32x32x16_bf16 v[112:127], v[152:155], v[148:151], v[112:127]
	v_lshl_add_u64 v[152:153], s[34:35], 0, v[200:201]
	global_load_dwordx4 v[152:155], v[152:153], off
	s_waitcnt lgkmcnt(1)
	v_mfma_f32_32x32x16_bf16 v[80:95], v[156:159], v[148:151], v[80:95]
	s_waitcnt vmcnt(5)
	v_and_b32_e32 v149, 0xffff0000, v144
	v_lshlrev_b32_e32 v148, 16, v144
	v_add_f32_e64 v128, v148, -v128
	v_add_f32_e64 v129, v149, -v129
	s_waitcnt vmcnt(4)
	v_and_b32_e32 v149, 0xffff0000, v10
	v_lshlrev_b32_e32 v148, 16, v10
	v_pk_add_f32 v[136:137], v[148:149], v[136:137] neg_lo:[0,1] neg_hi:[0,1]
	v_and_b32_e32 v149, 0xffff0000, v145
	v_lshlrev_b32_e32 v148, 16, v145
	v_and_b32_e32 v145, 0xffff0000, v11
	v_lshlrev_b32_e32 v144, 16, v11
	v_and_b32_e32 v11, 0xffff0000, v146
	v_lshlrev_b32_e32 v10, 16, v146
	v_pk_add_f32 v[10:11], v[10:11], v[132:133] neg_lo:[0,1] neg_hi:[0,1]
	v_and_b32_e32 v133, 0xffff0000, v12
	v_lshlrev_b32_e32 v132, 16, v12
	v_pk_add_f32 v[132:133], v[132:133], v[140:141] neg_lo:[0,1] neg_hi:[0,1]
	v_and_b32_e32 v141, 0xffff0000, v147
	v_lshlrev_b32_e32 v140, 16, v147
	v_pk_add_f32 v[130:131], v[148:149], v[130:131] neg_lo:[0,1] neg_hi:[0,1]
	v_pk_add_f32 v[134:135], v[140:141], v[134:135] neg_lo:[0,1] neg_hi:[0,1]
	v_cvt_pk_bf16_f32 v128, v128, v129
	v_cvt_pk_bf16_f32 v129, v130, v131
	v_cvt_pk_bf16_f32 v130, v10, v11
	v_cvt_pk_bf16_f32 v131, v134, v135
	v_and_b32_e32 v141, 0xffff0000, v13
	v_lshlrev_b32_e32 v140, 16, v13
	s_waitcnt lgkmcnt(0)
	v_mfma_f32_32x32x16_bf16 v[96:111], v[220:223], v[128:131], v[96:111]
	ds_read_b128 v[220:223], v217 offset:53280
	v_add_f32_e64 v138, v144, -v138
	v_add_f32_e64 v139, v145, -v139
	v_add_f32_e64 v140, v140, -v142
	v_add_f32_e64 v141, v141, -v143
	v_cvt_pk_bf16_f32 v10, v136, v137
	v_cvt_pk_bf16_f32 v11, v138, v139
	v_cvt_pk_bf16_f32 v12, v132, v133
	v_cvt_pk_bf16_f32 v13, v140, v141
	s_waitcnt vmcnt(3)
	v_and_b32_e32 v133, 0xffff0000, v6
	v_lshlrev_b32_e32 v132, 16, v6
	s_waitcnt lgkmcnt(0)
	v_mfma_f32_32x32x16_bf16 v[96:111], v[220:223], v[10:13], v[96:111]
	ds_read_b128 v[220:223], v217 offset:53312
	v_add_f32_e64 v112, v132, -v112
	v_add_f32_e64 v113, v133, -v113
	s_waitcnt vmcnt(2)
	v_and_b32_e32 v133, 0xffff0000, v2
	v_lshlrev_b32_e32 v132, 16, v2
	v_pk_add_f32 v[120:121], v[132:133], v[120:121] neg_lo:[0,1] neg_hi:[0,1]
	v_and_b32_e32 v133, 0xffff0000, v7
	v_lshlrev_b32_e32 v132, 16, v7
	v_and_b32_e32 v7, 0xffff0000, v3
	v_lshlrev_b32_e32 v6, 16, v3
	v_pk_add_f32 v[122:123], v[6:7], v[122:123] neg_lo:[0,1] neg_hi:[0,1]
	v_and_b32_e32 v3, 0xffff0000, v8
	v_lshlrev_b32_e32 v2, 16, v8
	v_and_b32_e32 v7, 0xffff0000, v4
	v_lshlrev_b32_e32 v6, 16, v4
	v_pk_add_f32 v[2:3], v[2:3], v[116:117] neg_lo:[0,1] neg_hi:[0,1]
	v_pk_add_f32 v[116:117], v[6:7], v[124:125] neg_lo:[0,1] neg_hi:[0,1]
	v_and_b32_e32 v7, 0xffff0000, v9
	v_lshlrev_b32_e32 v6, 16, v9
	v_pk_add_f32 v[114:115], v[132:133], v[114:115] neg_lo:[0,1] neg_hi:[0,1]
	v_pk_add_f32 v[118:119], v[6:7], v[118:119] neg_lo:[0,1] neg_hi:[0,1]
	v_and_b32_e32 v7, 0xffff0000, v5
	v_lshlrev_b32_e32 v6, 16, v5
	v_pk_add_f32 v[124:125], v[6:7], v[126:127] neg_lo:[0,1] neg_hi:[0,1]
	v_cvt_pk_bf16_f32 v6, v112, v113
	v_cvt_pk_bf16_f32 v7, v114, v115
	v_cvt_pk_bf16_f32 v8, v2, v3
	v_cvt_pk_bf16_f32 v9, v118, v119
	v_cvt_pk_bf16_f32 v2, v120, v121
	v_cvt_pk_bf16_f32 v3, v122, v123
	s_waitcnt lgkmcnt(0)
; #define MFMA32(a, b, c) __builtin_amdgcn_mfma_f32_32x32x16_bf16((a), (b), (c), 0, 0, 0)
; DI void phase_scan_c(int wv_, int vb_, int nvb_, char* ws_, const Ctx& p, char* smem, int half) {
;     ...
;       { const int ncn = nc < 31 ? nc + 1 : 31; SLOAD((size_t)blk * 32 + ncn) }
;     ...
; #pragma unroll
;       for (int mb = 0; mb < 4; ++mb) {
; #pragma unroll
;         for (int i = 0; i < 16; ++i) S[mb][i] *= egl;
; #pragma unroll
;         for (int tb = 0; tb < 2; ++tb)
; #pragma unroll
;           for (int s = 0; s < 2; ++s) {
;             bf16x8 a = *(const bf16x8*)(KTp + mb * 32 * 72 + tb * 32 + s * 16);
;             S[mb] = MFMA32(a, vb[tb][s], S[mb]);
;           }
;       }
	v_mfma_f32_32x32x16_bf16 v[96:111], v[220:223], v[6:9], v[96:111]
	ds_read_b128 v[220:223], v217 offset:53344
	v_cvt_pk_bf16_f32 v4, v116, v117
	v_cvt_pk_bf16_f32 v5, v124, v125
	v_lshl_add_u64 v[120:121], s[12:13], 0, v[188:189]
	v_lshl_add_u64 v[136:137], s[12:13], 0, v[190:191]
	v_lshl_add_u64 v[148:149], s[12:13], 0, v[192:193]
	s_add_u32 s12, s14, s18
	s_waitcnt lgkmcnt(0)
	v_mfma_f32_32x32x16_bf16 v[96:111], v[220:223], v[2:5], v[96:111]
	ds_read_b128 v[220:223], v217 offset:57856
	s_addc_u32 s13, s15, s19
	v_lshl_add_u64 v[112:113], s[34:35], 0, v[188:189]
	v_lshl_add_u64 v[116:117], s[44:45], 0, v[188:189]
	v_lshl_add_u64 v[124:125], s[34:35], 0, v[190:191]
	v_lshl_add_u64 v[132:133], s[44:45], 0, v[190:191]
	v_lshl_add_u64 v[140:141], s[34:35], 0, v[192:193]
	s_waitcnt lgkmcnt(0)
	v_mfma_f32_32x32x16_bf16 v[80:95], v[220:223], v[128:131], v[80:95]
	ds_read_b128 v[220:223], v217 offset:57888
	v_lshl_add_u64 v[144:145], s[44:45], 0, v[192:193]
	v_lshl_add_u64 v[156:157], s[44:45], 0, v[200:201]
	v_lshl_add_u64 v[164:165], s[12:13], 0, v[14:15]
	v_lshl_add_u64 v[168:169], s[12:13], 0, v[174:175]
	global_load_dwordx4 v[112:115], v[112:113], off
	v_cvt_pk_bf16_f32 v0, v96, s0
	s_waitcnt lgkmcnt(0)
	v_mfma_f32_32x32x16_bf16 v[80:95], v[220:223], v[10:13], v[80:95]
	ds_read_b128 v[220:223], v217 offset:57920
	global_load_dwordx4 v[116:119], v[116:117], off
	s_add_u32 s4, s4, 4
	global_load_dwordx4 v[120:123], v[120:121], off
	s_addc_u32 s5, s5, 0
	global_load_dwordx4 v[124:127], v[124:125], off
	s_waitcnt lgkmcnt(0)
	v_mfma_f32_32x32x16_bf16 v[80:95], v[220:223], v[6:9], v[80:95]
	ds_read_b128 v[220:223], v217 offset:57952
	global_load_dwordx4 v[132:135], v[132:133], off
	s_nop 0
	global_load_dwordx4 v[136:139], v[136:137], off
	s_nop 0
	global_load_dwordx4 v[140:143], v[140:141], off
	s_nop 0
	global_load_dwordx4 v[144:147], v[144:145], off
	s_waitcnt lgkmcnt(0)
	v_mfma_f32_32x32x16_bf16 v[80:95], v[220:223], v[2:5], v[80:95]
	global_load_dwordx4 v[148:151], v[148:149], off
	s_nop 0
	global_load_dwordx4 v[156:159], v[156:157], off
	s_nop 0
	global_load_dwordx4 v[164:167], v[164:165], off
	s_nop 0
	global_load_dwordx4 v[168:171], v[168:169], off
	ds_read_b128 v[220:223], v217 offset:34816
	ds_read_b128 v[224:227], v217 offset:34848
	s_waitcnt lgkmcnt(1)
	v_mfma_f32_32x32x16_bf16 v[16:31], v[220:223], v[128:131], v[16:31]
	ds_read_b128 v[220:223], v217 offset:34880
	s_waitcnt lgkmcnt(1)
	v_mfma_f32_32x32x16_bf16 v[16:31], v[224:227], v[10:13], v[16:31]
	s_waitcnt lgkmcnt(0)
	v_mfma_f32_32x32x16_bf16 v[16:31], v[220:223], v[6:9], v[16:31]
	ds_read_b128 v[220:223], v217 offset:34912
	s_waitcnt lgkmcnt(0)
	v_mfma_f32_32x32x16_bf16 v[16:31], v[220:223], v[2:5], v[16:31]
	ds_read_b128 v[220:223], v217 offset:39424
	s_waitcnt lgkmcnt(0)
	v_mfma_f32_32x32x16_bf16 v[32:47], v[220:223], v[128:131], v[32:47]
	ds_read_b128 v[220:223], v217 offset:39456
	s_waitcnt lgkmcnt(0)
	v_mfma_f32_32x32x16_bf16 v[32:47], v[220:223], v[10:13], v[32:47]
	ds_read_b128 v[220:223], v217 offset:39488
	s_waitcnt lgkmcnt(0)
	v_mfma_f32_32x32x16_bf16 v[32:47], v[220:223], v[6:9], v[32:47]
	ds_read_b128 v[220:223], v217 offset:39520
	s_waitcnt lgkmcnt(0)
	v_mfma_f32_32x32x16_bf16 v[32:47], v[220:223], v[2:5], v[32:47]
	ds_read_b128 v[220:223], v217 offset:44032
	s_waitcnt lgkmcnt(0)
	v_mfma_f32_32x32x16_bf16 v[48:63], v[220:223], v[128:131], v[48:63]
	ds_read_b128 v[220:223], v217 offset:44064
	s_waitcnt lgkmcnt(0)
	v_mfma_f32_32x32x16_bf16 v[48:63], v[220:223], v[10:13], v[48:63]
	ds_read_b128 v[220:223], v217 offset:44096
	s_waitcnt lgkmcnt(0)
	v_mfma_f32_32x32x16_bf16 v[48:63], v[220:223], v[6:9], v[48:63]
	ds_read_b128 v[220:223], v217 offset:44128
	s_waitcnt lgkmcnt(0)
	v_mfma_f32_32x32x16_bf16 v[48:63], v[220:223], v[2:5], v[48:63]
	ds_read_b128 v[220:223], v217 offset:48640
	s_waitcnt lgkmcnt(0)
	v_mfma_f32_32x32x16_bf16 v[64:79], v[220:223], v[128:131], v[64:79]
	ds_read_b128 v[128:131], v217 offset:48672
	s_waitcnt lgkmcnt(0)
	v_mfma_f32_32x32x16_bf16 v[64:79], v[128:131], v[10:13], v[64:79]
	ds_read_b128 v[10:13], v217 offset:48704
	s_waitcnt lgkmcnt(0)
	v_mfma_f32_32x32x16_bf16 v[64:79], v[10:13], v[6:9], v[64:79]
	ds_read_b128 v[6:9], v217 offset:48736
	s_waitcnt lgkmcnt(0)
; DI u16 f2bf(float x) { return (u16)(pk2bf(x, 0.f) & 0xffffu); }
; DI int crow(int i, int h) { return (i & 3) + 8 * (i >> 2) + 4 * h; }
; DI void phase_scan_c(int wv_, int vb_, int nvb_, char* ws_, const Ctx& p, char* smem, int half) {
;     ...
;       u16* op = O + ((size_t)b * SEQ + (size_t)(half * 32 + nc) * 64) * 1024 + hd * 128 + dv0 + c;
; #pragma unroll
;       for (int tb = 0; tb < 2; ++tb)
; #pragma unroll
;         for (int i = 0; i < 16; ++i) op[(size_t)(tb * 32 + crow(i, h)) * 1024] = f2bf(Oa[tb][i]);
;       __syncthreads();
;       SWRITE()
;       __syncthreads();
;     }
	v_mfma_f32_32x32x16_bf16 v[64:79], v[6:9], v[2:5], v[64:79]
	v_lshl_add_u64 v[2:3], v[184:185], 0, s[16:17]
	v_add_co_u32_e32 v4, vcc, s52, v2
	v_lshl_add_u64 v[184:185], v[184:185], 0, s[96:97]
	s_nop 0
	v_addc_co_u32_e32 v5, vcc, 0, v3, vcc
	v_add_co_u32_e32 v6, vcc, s62, v2
	s_nop 1
	v_addc_co_u32_e32 v7, vcc, 0, v3, vcc
	global_store_short v[6:7], v0, off offset:-4096
	v_cvt_pk_bf16_f32 v0, v97, s0
	global_store_short v[4:5], v0, off offset:2048
	v_cvt_pk_bf16_f32 v0, v98, s0
	v_add_co_u32_e32 v4, vcc, s63, v2
	global_store_short v[6:7], v0, off
	v_cvt_pk_bf16_f32 v0, v99, s0
	v_addc_co_u32_e32 v5, vcc, 0, v3, vcc
	global_store_short v[6:7], v0, off offset:2048
	v_add_co_u32_e32 v6, vcc, s64, v2
	v_cvt_pk_bf16_f32 v0, v100, s0
	s_nop 0
	v_addc_co_u32_e32 v7, vcc, 0, v3, vcc
	global_store_short v[6:7], v0, off offset:-4096
	v_cvt_pk_bf16_f32 v0, v101, s0
	global_store_short v[4:5], v0, off offset:2048
	v_cvt_pk_bf16_f32 v0, v102, s0
	v_add_co_u32_e32 v4, vcc, s65, v2
	global_store_short v[6:7], v0, off
	v_cvt_pk_bf16_f32 v0, v103, s0
	v_addc_co_u32_e32 v5, vcc, 0, v3, vcc
	global_store_short v[6:7], v0, off offset:2048
	v_add_co_u32_e32 v6, vcc, s68, v2
	v_cvt_pk_bf16_f32 v0, v104, s0
	s_nop 0
	v_addc_co_u32_e32 v7, vcc, 0, v3, vcc
	global_store_short v[6:7], v0, off offset:-4096
	v_cvt_pk_bf16_f32 v0, v105, s0
	global_store_short v[4:5], v0, off offset:2048
	v_cvt_pk_bf16_f32 v0, v106, s0
	v_add_co_u32_e32 v4, vcc, s69, v2
	global_store_short v[6:7], v0, off
	v_cvt_pk_bf16_f32 v0, v107, s0
	v_addc_co_u32_e32 v5, vcc, 0, v3, vcc
	global_store_short v[6:7], v0, off offset:2048
	v_add_co_u32_e32 v6, vcc, s72, v2
	v_cvt_pk_bf16_f32 v0, v108, s0
	s_nop 0
	v_addc_co_u32_e32 v7, vcc, 0, v3, vcc
	global_store_short v[6:7], v0, off offset:-4096
	v_cvt_pk_bf16_f32 v0, v109, s0
	global_store_short v[4:5], v0, off offset:2048
	v_cvt_pk_bf16_f32 v0, v110, s0
	v_add_co_u32_e32 v4, vcc, s73, v2
	global_store_short v[6:7], v0, off
	v_cvt_pk_bf16_f32 v0, v111, s0
	v_addc_co_u32_e32 v5, vcc, 0, v3, vcc
	global_store_short v[6:7], v0, off offset:2048
	v_add_co_u32_e32 v6, vcc, s76, v2
	v_cvt_pk_bf16_f32 v0, v80, s0
	s_nop 0
	v_addc_co_u32_e32 v7, vcc, 0, v3, vcc
	global_store_short v[6:7], v0, off offset:-4096
	v_cvt_pk_bf16_f32 v0, v81, s0
	global_store_short v[4:5], v0, off offset:2048
	v_cvt_pk_bf16_f32 v0, v82, s0
	v_add_co_u32_e32 v4, vcc, s77, v2
	global_store_short v[6:7], v0, off
	v_cvt_pk_bf16_f32 v0, v83, s0
	v_addc_co_u32_e32 v5, vcc, 0, v3, vcc
	global_store_short v[6:7], v0, off offset:2048
	v_add_co_u32_e32 v6, vcc, s88, v2
	v_cvt_pk_bf16_f32 v0, v84, s0
	s_nop 0
	v_addc_co_u32_e32 v7, vcc, 0, v3, vcc
	global_store_short v[6:7], v0, off offset:-4096
	v_cvt_pk_bf16_f32 v0, v85, s0
	global_store_short v[4:5], v0, off offset:2048
	v_cvt_pk_bf16_f32 v0, v86, s0
	v_add_co_u32_e32 v4, vcc, s89, v2
	global_store_short v[6:7], v0, off
	v_cvt_pk_bf16_f32 v0, v87, s0
	v_addc_co_u32_e32 v5, vcc, 0, v3, vcc
	global_store_short v[6:7], v0, off offset:2048
	v_add_co_u32_e32 v6, vcc, s90, v2
	v_cvt_pk_bf16_f32 v0, v88, s0
	s_nop 0
	v_addc_co_u32_e32 v7, vcc, 0, v3, vcc
	global_store_short v[6:7], v0, off offset:-4096
	v_cvt_pk_bf16_f32 v0, v89, s0
	global_store_short v[4:5], v0, off offset:2048
	v_add_co_u32_e32 v4, vcc, s91, v2
	v_cvt_pk_bf16_f32 v0, v90, s0
	s_nop 0
	v_addc_co_u32_e32 v5, vcc, 0, v3, vcc
	global_store_short v[6:7], v0, off
	v_cvt_pk_bf16_f32 v0, v91, s0
	v_add_co_u32_e32 v2, vcc, s94, v2
	global_store_short v[6:7], v0, off offset:2048
	v_cvt_pk_bf16_f32 v0, v92, s0
	v_addc_co_u32_e32 v3, vcc, 0, v3, vcc
	global_store_short v[2:3], v0, off offset:-4096
	v_cvt_pk_bf16_f32 v0, v93, s0
	global_store_short v[4:5], v0, off offset:2048
	v_cvt_pk_bf16_f32 v0, v94, s0
	v_cmp_eq_u32_e32 vcc, 0, v218
	global_store_short v[2:3], v0, off
	v_cvt_pk_bf16_f32 v0, v95, s0
	s_and_b64 vcc, exec, vcc
	global_store_short v[2:3], v0, off offset:2048
	s_barrier
	s_waitcnt vmcnt(43)
	ds_write_b128 v176, v[112:115]
	s_waitcnt vmcnt(42)
	ds_write_b128 v176, v[116:119] offset:17408
	s_waitcnt vmcnt(41)
	ds_write_b128 v177, v[120:123] offset:34816
	s_waitcnt vmcnt(40)
	ds_write_b128 v178, v[124:127]
	s_waitcnt vmcnt(39)
	ds_write_b128 v178, v[132:135] offset:17408
	s_waitcnt vmcnt(38)
	ds_write_b128 v179, v[136:139] offset:34816
	s_waitcnt vmcnt(37)
	ds_write_b128 v180, v[140:143]
	s_waitcnt vmcnt(36)
	ds_write_b128 v180, v[144:147] offset:17408
	s_waitcnt vmcnt(35)
	ds_write_b128 v181, v[148:151] offset:34816
	ds_write_b128 v182, v[152:155]
	s_waitcnt vmcnt(34)
	ds_write_b128 v182, v[156:159] offset:17408
	ds_write_b128 v183, v[160:163] offset:34816
	s_waitcnt vmcnt(33)
	ds_write_b128 v202, v[164:167] offset:53248
	s_waitcnt vmcnt(32)
	ds_write_b128 v203, v[168:171] offset:53248
	s_waitcnt lgkmcnt(0)
	s_barrier
	s_cbranch_vccz .LBB0_232
	s_mov_b32 s52, 0x6600000
	s_andn2_b64 vcc, exec, s[60:61]
	s_cbranch_vccnz .LBB0_235
; DI void phase_convert(int wv_, int vb_, int nvb_, char* ws_, const Ctx& p, char* smem) {
;   float* tile = (float*)smem;
;   const int tid = tidx(wv_);
;   const int ty = tid >> 4, tx = tid & 15;
;   constexpr int total = wTileStart(16);
;   const int trips_ = (total + nvb_ - 1) / nvb_;
; DI void phase_scan_c(int wv_, int vb_, int nvb_, char* ws_, const Ctx& p, char* smem, int half) {
;     ...
;     if (half == 0) {
; #pragma unroll
;       for (int mb = 0; mb < 4; ++mb)
; #pragma unroll
;         for (int i = 0; i < 16; ++i) stp[(mb * 16 + i) * 64] = S[mb][i];
;     }
	s_movk_i32 s0, 0x1000
	v_add_co_u32_e32 v2, vcc, s0, v172
	s_movk_i32 s0, 0x2000
	s_nop 0
	v_addc_co_u32_e32 v3, vcc, 0, v173, vcc
	v_add_co_u32_e32 v4, vcc, s0, v172
	s_movk_i32 s0, 0x3000
	s_nop 0
	v_addc_co_u32_e32 v5, vcc, 0, v173, vcc
	global_store_dword v[172:173], v16, off
	global_store_dword v[172:173], v17, off offset:256
	global_store_dword v[172:173], v18, off offset:512
	global_store_dword v[172:173], v19, off offset:768
	global_store_dword v[172:173], v20, off offset:1024
	global_store_dword v[172:173], v21, off offset:1280
	global_store_dword v[172:173], v22, off offset:1536
	global_store_dword v[172:173], v23, off offset:1792
	global_store_dword v[172:173], v24, off offset:2048
	global_store_dword v[172:173], v25, off offset:2304
	global_store_dword v[172:173], v26, off offset:2560
	global_store_dword v[172:173], v27, off offset:2816
	global_store_dword v[172:173], v28, off offset:3072
	global_store_dword v[172:173], v29, off offset:3328
	global_store_dword v[172:173], v30, off offset:3584
	global_store_dword v[172:173], v31, off offset:3840
	global_store_dword v[4:5], v32, off offset:-4096
	global_store_dword v[2:3], v33, off offset:256
	global_store_dword v[2:3], v34, off offset:512
	global_store_dword v[2:3], v35, off offset:768
	global_store_dword v[2:3], v36, off offset:1024
	global_store_dword v[2:3], v37, off offset:1280
	global_store_dword v[2:3], v38, off offset:1536
	global_store_dword v[2:3], v39, off offset:1792
	global_store_dword v[2:3], v40, off offset:2048
	global_store_dword v[2:3], v41, off offset:2304
	global_store_dword v[2:3], v42, off offset:2560
	global_store_dword v[2:3], v43, off offset:2816
	global_store_dword v[2:3], v44, off offset:3072
	global_store_dword v[2:3], v45, off offset:3328
	global_store_dword v[2:3], v46, off offset:3584
	global_store_dword v[2:3], v47, off offset:3840
	global_store_dword v[4:5], v48, off
	global_store_dword v[4:5], v49, off offset:256
	global_store_dword v[4:5], v50, off offset:512
	global_store_dword v[4:5], v51, off offset:768
	global_store_dword v[4:5], v52, off offset:1024
	global_store_dword v[4:5], v53, off offset:1280
	global_store_dword v[4:5], v54, off offset:1536
	global_store_dword v[4:5], v55, off offset:1792
	global_store_dword v[4:5], v56, off offset:2048
	global_store_dword v[4:5], v57, off offset:2304
	global_store_dword v[4:5], v58, off offset:2560
	global_store_dword v[4:5], v59, off offset:2816
	global_store_dword v[4:5], v60, off offset:3072
	global_store_dword v[4:5], v61, off offset:3328
	global_store_dword v[4:5], v62, off offset:3584
	global_store_dword v[4:5], v63, off offset:3840
	v_add_co_u32_e32 v2, vcc, s0, v172
	s_nop 1
	v_addc_co_u32_e32 v3, vcc, 0, v173, vcc
	global_store_dword v[2:3], v64, off
	global_store_dword v[2:3], v65, off offset:256
	global_store_dword v[2:3], v66, off offset:512
	global_store_dword v[2:3], v67, off offset:768
	global_store_dword v[2:3], v68, off offset:1024
	global_store_dword v[2:3], v69, off offset:1280
	global_store_dword v[2:3], v70, off offset:1536
	global_store_dword v[2:3], v71, off offset:1792
	global_store_dword v[2:3], v72, off offset:2048
	global_store_dword v[2:3], v73, off offset:2304
	global_store_dword v[2:3], v74, off offset:2560
	global_store_dword v[2:3], v75, off offset:2816
	global_store_dword v[2:3], v76, off offset:3072
	global_store_dword v[2:3], v77, off offset:3328
	global_store_dword v[2:3], v78, off offset:3584
	global_store_dword v[2:3], v79, off offset:3840
	s_branch .LBB0_235
.Lcvt_late_chk:
	s_nop 0
	s_nop 0
	v_readlane_b32 s0, v254, 14
	s_cmp_lt_u32 s0, 0x80
	s_cbranch_scc1 .LBB0_235
	s_mov_b64 s[56:57], s[54:55]
	v_readlane_b32 s54, v254, 46
	v_readlane_b32 s55, v254, 47
	v_readlane_b32 s44, v254, 14
	v_readlane_b32 s35, v254, 56
	s_sub_i32 s44, s44, 128
	s_sub_i32 s35, s35, 128
	s_mov_b32 s10, s33
	v_lshl_add_u32 v81, s10, 6, v204
	v_lshrrev_b32_e32 v74, 4, v81
	v_and_b32_e32 v75, 15, v81
	v_lshlrev_b32_e32 v75, 2, v75
	v_lshrrev_b32_e32 v78, 2, v81
	v_and_b32_e32 v79, 3, v81
	v_mul_u32_u24_e32 v76, 65, v74
	v_add_u32_e32 v76, v76, v75
	v_lshl_add_u32 v76, v76, 2, v214
	v_mul_u32_u24_e32 v77, 0x410, v79
	v_add_u32_e32 v77, v77, v78
	v_lshl_add_u32 v77, v77, 2, v214
	v_lshlrev_b32_e32 v79, 5, v79
	s_mov_b32 s34, 0
; DI u16 f2bf(float x) { return (u16)(pk2bf(x, 0.f) & 0xffffu); }
; #define WSEL(i) if (t >= wTileStart(i)) { K = cK[i]; N = cN[i]; base = wTileStart(i); off = wOff(i); soff = cSrcOff[i]; bi = cBase[i]; }
; #define CVT_LOAD(C, V) { _Pragma("unroll") for (int i = 0; i < 4; ++i) { const int n_ = (C).n0 + tx * 4; \
;     V[i] = (n_ < (C).N) ? *(const float4*)((C).src + (size_t)((C).k0 + ty + 16 * i) * (C).N + n_) : make_float4(0.f, 0.f, 0.f, 0.f); } }
; DI CvtTile cvt_locate(const Ctx& p, int t) {
;   int K = cK[0], N = cN[0], base = 0; unsigned off = 0, soff = 0; int bi = 0;
;     ...
;   WSEL(1) WSEL(2) WSEL(3) WSEL(4) WSEL(5) WSEL(6) WSEL(7) WSEL(8) WSEL(9) WSEL(10) WSEL(11) WSEL(12) WSEL(13) WSEL(14) WSEL(15)
;     ...
;   const float* src = p.wbase[0];
; #pragma unroll
;   for (int q = 1; q < 8; ++q) if (bi == q) src = p.wbase[q];
;   const int lt = t - base, nkt = K / 64;
;   CvtTile c; c.src = src + soff; c.K = K; c.N = N; c.k0 = (lt % nkt) * 64; c.n0 = (lt / nkt) * 64; c.off = off;
;   return c;
; }
; DI void phase_convert(int wv_, int vb_, int nvb_, char* ws_, const Ctx& p, char* smem) {
;   float* tile = (float*)smem;
;   const int tid = tidx(wv_);
;   const int ty = tid >> 4, tx = tid & 15;
;   constexpr int total = wTileStart(16);
;   const int trips_ = (total + nvb_ - 1) / nvb_;
;     ...
;   CvtTile cur = cvt_locate(p, (vb_ < total) ? vb_ : total - 1);
;   float4 v[4];
;   CVT_LOAD(cur, v)
;   for (int k_ = 0; k_ < trips_; ++k_) {
;     const int tn = vb_ + (k_ + 1) * nvb_;
;     const CvtTile nxt = cvt_locate(p, (tn < total) ? tn : total - 1);
;     float4 vn[4];
;     CVT_LOAD(nxt, vn)
; #pragma unroll
;     for (int i = 0; i < 4; ++i) { float* d = tile + (ty + 16 * i) * 65 + tx * 4; d[0] = v[i].x; d[1] = v[i].y; d[2] = v[i].z; d[3] = v[i].w; }
;     __syncthreads();
;     {
;       const int n = tid >> 2, kq = tid & 3;
;       bf16x8 o0, o1;
; #pragma unroll
;       for (int j = 0; j < 8; ++j) { o0[j] = (short)f2bf(tile[(kq * 16 + j) * 65 + n]); o1[j] = (short)f2bf(tile[(kq * 16 + 8 + j) * 65 + n]); }
;       u16* dst = (u16*)(ws_ + WS_WT) + (size_t)cur.off + (size_t)(cur.n0 + n) * cur.K + cur.k0 + kq * 16;
;       *(bf16x8*)dst = o0; *(bf16x8*)(dst + 8) = o1;
;     }
;     __syncthreads();
.Lcvtb_loop:
	s_mul_i32 s52, s34, s35
	s_add_i32 s52, s52, s44
	s_min_u32 s52, s52, 0xcff
	s_mov_b32 s0, 4
	s_mov_b32 s1, 0x1200
	s_mov_b32 s2, 0
	s_mov_b32 s3, 0x480000
	s_mov_b32 s7, 0x480000
	s_mov_b32 s11, 0
	s_cmp_ge_u32 s52, 0x480
	s_cselect_b32 s0, 3, s0
	s_cselect_b32 s1, 0x400, s1
	s_cselect_b32 s2, 1, s2
	s_cselect_b32 s3, 0x80000, s3
	s_cselect_b32 s7, 0x980000, s7
	s_cselect_b32 s11, 0x480, s11
	s_cmp_ge_u32 s52, 0x500
	s_cselect_b32 s0, 4, s0
	s_cselect_b32 s1, 0x1000, s1
	s_cselect_b32 s2, 6, s2
	s_cselect_b32 s3, 0xc00000, s3
	s_cselect_b32 s7, 0x1e80000, s7
	s_cselect_b32 s11, 0x500, s11
	s_cmp_ge_u32 s52, 0x900
	s_cselect_b32 s0, 6, s0
	s_cselect_b32 s1, 0x400, s1
	s_cselect_b32 s2, 7, s2
	s_cselect_b32 s3, 0xc00000, s3
	s_cselect_b32 s7, 0x2e80000, s7
	s_cselect_b32 s11, 0x900, s11
	s_lshl_b32 s15, s2, 3
	s_add_i32 s15, s15, 0x60
	s_load_dwordx2 s[18:19], s[54:55], s15
	s_sub_i32 s15, s52, s11
	s_lshl_b32 s2, 1, s0
	s_add_i32 s2, s2, -1
	s_and_b32 s2, s15, s2
	s_lshl_b32 s2, s2, 6
	s_lshr_b32 s15, s15, s0
	s_lshl_b32 s15, s15, 6
	s_mov_b32 s6, s0
	s_add_i32 s11, s0, 6
	s_lshl_b32 s11, s15, s11
	s_add_i32 s11, s11, s7
	s_add_i32 s11, s11, s2
	s_lshl_b32 s11, s11, 1
	s_add_u32 s4, s78, s11
	s_addc_u32 s5, s79, 0
	s_mul_i32 s7, s2, s1
	s_add_i32 s7, s7, s3
	s_add_i32 s7, s7, s15
	s_lshl_b32 s7, s7, 2
	s_lshl_b32 s3, s1, 6
	v_mul_u32_u24_e32 v81, s1, v74
	v_add_u32_e32 v81, v81, v75
	v_lshlrev_b32_e32 v80, 2, v81
	v_add_u32_e32 v81, s15, v75
	v_mov_b32_e32 v2, 0
	v_mov_b32_e32 v3, 0
	v_mov_b32_e32 v4, 0
	v_mov_b32_e32 v5, 0
	v_mov_b32_e32 v6, 0
	v_mov_b32_e32 v7, 0
	v_mov_b32_e32 v8, 0
	v_mov_b32_e32 v9, 0
	v_mov_b32_e32 v10, 0
	v_mov_b32_e32 v11, 0
	v_mov_b32_e32 v12, 0
	v_mov_b32_e32 v13, 0
	v_mov_b32_e32 v14, 0
	v_mov_b32_e32 v15, 0
	v_mov_b32_e32 v16, 0
	v_mov_b32_e32 v17, 0
	s_waitcnt lgkmcnt(0)
	s_add_u32 s18, s18, s7
	s_addc_u32 s19, s19, 0
	v_cmp_gt_u32_e32 vcc, s1, v81
	s_and_saveexec_b64 s[100:101], vcc
	global_load_dwordx4 v[2:5], v80, s[18:19]
	s_add_u32 s18, s18, s3
	s_addc_u32 s19, s19, 0
	global_load_dwordx4 v[6:9], v80, s[18:19]
	s_add_u32 s18, s18, s3
	s_addc_u32 s19, s19, 0
	global_load_dwordx4 v[10:13], v80, s[18:19]
	s_add_u32 s18, s18, s3
	s_addc_u32 s19, s19, 0
	global_load_dwordx4 v[14:17], v80, s[18:19]
	s_mov_b64 exec, s[100:101]
	s_waitcnt vmcnt(0)
	ds_write_b32 v76, v2
	ds_write_b32 v76, v3 offset:4
	ds_write_b32 v76, v4 offset:8
	ds_write_b32 v76, v5 offset:12
	ds_write_b32 v76, v6 offset:4160
	ds_write_b32 v76, v7 offset:4164
	ds_write_b32 v76, v8 offset:4168
	ds_write_b32 v76, v9 offset:4172
	ds_write_b32 v76, v10 offset:8320
	ds_write_b32 v76, v11 offset:8324
	ds_write_b32 v76, v12 offset:8328
	ds_write_b32 v76, v13 offset:8332
	ds_write_b32 v76, v14 offset:12480
	ds_write_b32 v76, v15 offset:12484
	ds_write_b32 v76, v16 offset:12488
	ds_write_b32 v76, v17 offset:12492
	s_waitcnt lgkmcnt(0)
	s_barrier
	ds_read_b32 v50, v77
	ds_read_b32 v51, v77 offset:260
	ds_read_b32 v52, v77 offset:520
	ds_read_b32 v53, v77 offset:780
	ds_read_b32 v54, v77 offset:1040
	ds_read_b32 v55, v77 offset:1300
	ds_read_b32 v56, v77 offset:1560
	ds_read_b32 v57, v77 offset:1820
	ds_read_b32 v58, v77 offset:2080
	ds_read_b32 v59, v77 offset:2340
	ds_read_b32 v60, v77 offset:2600
	ds_read_b32 v61, v77 offset:2860
	ds_read_b32 v62, v77 offset:3120
	ds_read_b32 v63, v77 offset:3380
	ds_read_b32 v64, v77 offset:3640
	ds_read_b32 v65, v77 offset:3900
	s_add_i32 s15, s6, 7
	v_lshlrev_b32_e32 v82, s15, v78
	v_add_u32_e32 v82, v82, v79
	s_waitcnt lgkmcnt(0)
	v_cvt_pk_bf16_f32 v66, v50, v51
	v_cvt_pk_bf16_f32 v67, v52, v53
	v_cvt_pk_bf16_f32 v68, v54, v55
	v_cvt_pk_bf16_f32 v69, v56, v57
	v_cvt_pk_bf16_f32 v70, v58, v59
	v_cvt_pk_bf16_f32 v71, v60, v61
	v_cvt_pk_bf16_f32 v72, v62, v63
	v_cvt_pk_bf16_f32 v73, v64, v65
	global_store_dwordx4 v82, v[66:69], s[4:5]
	global_store_dwordx4 v82, v[70:73], s[4:5] offset:16
	s_barrier
	s_add_i32 s34, s34, 1
	s_mul_i32 s15, s34, s35
	s_cmp_lt_u32 s15, 0xd00
	s_cbranch_scc1 .Lcvtb_loop
	s_waitcnt vmcnt(0)
	s_mov_b64 s[54:55], s[56:57]
	s_mov_b32 s52, 0x6600000

; DI u16 f2bf(float x) { return (u16)(pk2bf(x, 0.f) & 0xffffu); }
; #define CVT_LOAD(C, V) { _Pragma("unroll") for (int i = 0; i < 4; ++i) { const int n_ = (C).n0 + tx * 4; \
;     V[i] = (n_ < (C).N) ? *(const float4*)((C).src + (size_t)((C).k0 + ty + 16 * i) * (C).N + n_) : make_float4(0.f, 0.f, 0.f, 0.f); } }
; DI void phase_convert(int wv_, int vb_, int nvb_, char* ws_, const Ctx& p, char* smem) {
;   float* tile = (float*)smem;
;   const int tid = tidx(wv_);
;   const int ty = tid >> 4, tx = tid & 15;
;   constexpr int total = wTileStart(16);
;   const int trips_ = (total + nvb_ - 1) / nvb_;
;     ...
;   CvtTile cur = cvt_locate(p, (vb_ < total) ? vb_ : total - 1);
;   float4 v[4];
;   CVT_LOAD(cur, v)
;   for (int k_ = 0; k_ < trips_; ++k_) {
;     const int tn = vb_ + (k_ + 1) * nvb_;
;     const CvtTile nxt = cvt_locate(p, (tn < total) ? tn : total - 1);
;     float4 vn[4];
;     CVT_LOAD(nxt, vn)
; #pragma unroll
;     for (int i = 0; i < 4; ++i) { float* d = tile + (ty + 16 * i) * 65 + tx * 4; d[0] = v[i].x; d[1] = v[i].y; d[2] = v[i].z; d[3] = v[i].w; }
;     __syncthreads();
;     {
;       const int n = tid >> 2, kq = tid & 3;
;       bf16x8 o0, o1;
; #pragma unroll
;       for (int j = 0; j < 8; ++j) { o0[j] = (short)f2bf(tile[(kq * 16 + j) * 65 + n]); o1[j] = (short)f2bf(tile[(kq * 16 + 8 + j) * 65 + n]); }
;       u16* dst = (u16*)(ws_ + WS_WT) + (size_t)cur.off + (size_t)(cur.n0 + n) * cur.K + cur.k0 + kq * 16;
;       *(bf16x8*)dst = o0; *(bf16x8*)(dst + 8) = o1;
;     }
;     __syncthreads();
;     cur = nxt;
; #pragma unroll
;     for (int i = 0; i < 4; ++i) v[i] = vn[i];
;   }
;     ...
; }
.LBB0_764:
	s_andn2_b64 vcc, exec, s[2:3]
	s_cbranch_vccnz .LBB0_848
	v_readlane_b32 s54, v254, 46
	s_cmp_lg_u32 s23, 1
	s_mov_b64 s[2:3], -1
	v_readlane_b32 s55, v254, 47
	s_movk_i32 s45, 0xf000
	v_readlane_b32 s0, v254, 56
	s_movk_i32 s56, 0xa000
	s_movk_i32 s57, 0xb000
	s_movk_i32 s62, 0xc000
	s_movk_i32 s63, 0xd000
	s_movk_i32 s64, 0xe000
	s_movk_i32 s65, 0x7fff
	v_readlane_b32 s1, v254, 57
	s_cbranch_scc0 .LBB0_843
	v_readlane_b32 s44, v254, 14
	v_readlane_b32 s35, v254, 56
	s_mov_b32 s10, s33
	v_lshl_add_u32 v81, s10, 6, v204
	v_lshrrev_b32_e32 v74, 4, v81
	v_and_b32_e32 v75, 15, v81
	v_lshlrev_b32_e32 v75, 2, v75
	v_lshrrev_b32_e32 v78, 2, v81
	v_and_b32_e32 v79, 3, v81
	v_mul_u32_u24_e32 v76, 65, v74
	v_add_u32_e32 v76, v76, v75
	v_lshl_add_u32 v76, v76, 2, v214
	v_mul_u32_u24_e32 v77, 0x410, v79
	v_add_u32_e32 v77, v77, v78
	v_lshl_add_u32 v77, v77, 2, v214
	v_lshlrev_b32_e32 v79, 5, v79
	s_mov_b32 s34, 0
.Lcvta_loop:
	s_mul_i32 s52, s34, s35
	s_add_i32 s52, s52, s44
	s_min_u32 s52, s52, 0x257f
	s_mov_b32 s0, 4
	s_mov_b32 s1, 0x1200
	s_mov_b32 s2, 0
	s_mov_b32 s3, 0
	s_mov_b32 s7, 0
	s_mov_b32 s11, 0
	s_cmp_ge_u32 s52, 0x480
	s_cselect_b32 s0, 3, s0
	s_cselect_b32 s1, 0x400, s1
	s_cselect_b32 s2, 1, s2
	s_cselect_b32 s3, 0, s3
	s_cselect_b32 s7, 0x900000, s7
	s_cselect_b32 s11, 0x480, s11
	s_cmp_ge_u32 s52, 0x500
	s_cselect_b32 s0, 4, s0
	s_cselect_b32 s1, 0x848, s1
	s_cselect_b32 s2, 2, s2
	s_cselect_b32 s3, 0, s3
	s_cselect_b32 s7, 0xa00000, s7
	s_cselect_b32 s11, 0x500, s11
	s_cmp_ge_u32 s52, 0x740
	s_cselect_b32 s0, 4, s0
	s_cselect_b32 s1, 0x400, s1
	s_cselect_b32 s2, 3, s2
	s_cselect_b32 s3, 0, s3
	s_cselect_b32 s7, 0xc40000, s7
	s_cselect_b32 s11, 0x740, s11
	s_cmp_ge_u32 s52, 0x840
	s_cselect_b32 s0, 4, s0
	s_cselect_b32 s1, 0x1010, s1
	s_cselect_b32 s2, 4, s2
	s_cselect_b32 s3, 0, s3
	s_cselect_b32 s7, 0xd40000, s7
	s_cselect_b32 s11, 0x840, s11
	s_cmp_ge_u32 s52, 0xc80
	s_cselect_b32 s0, 4, s0
	s_cselect_b32 s1, 0x400, s1
	s_cselect_b32 s2, 5, s2
	s_cselect_b32 s3, 0, s3
	s_cselect_b32 s7, 0x1180000, s7
	s_cselect_b32 s11, 0xc80, s11
	s_cmp_ge_u32 s52, 0xd80
	s_cselect_b32 s0, 4, s0
	s_cselect_b32 s1, 0x1000, s1
	s_cselect_b32 s2, 6, s2
	s_cselect_b32 s3, 0, s3
	s_cselect_b32 s7, 0x1280000, s7
	s_cselect_b32 s11, 0xd80, s11
	s_cmp_ge_u32 s52, 0x1180
	s_cselect_b32 s0, 4, s0
	s_cselect_b32 s1, 0x1000, s1
	s_cselect_b32 s2, 6, s2
	s_cselect_b32 s3, 0x400000, s3
	s_cselect_b32 s7, 0x1680000, s7
	s_cselect_b32 s11, 0x1180, s11
	s_cmp_ge_u32 s52, 0x1580
	s_cselect_b32 s0, 4, s0
	s_cselect_b32 s1, 0x1000, s1
	s_cselect_b32 s2, 6, s2
	s_cselect_b32 s3, 0x800000, s3
	s_cselect_b32 s7, 0x1a80000, s7
	s_cselect_b32 s11, 0x1580, s11
	s_cmp_ge_u32 s52, 0x1980
	s_cselect_b32 s0, 6, s0
	s_cselect_b32 s1, 0x400, s1
	s_cselect_b32 s2, 7, s2
	s_cselect_b32 s3, 0, s3
	s_cselect_b32 s7, 0x2280000, s7
	s_cselect_b32 s11, 0x1980, s11
	s_cmp_ge_u32 s52, 0x1d80
	s_cselect_b32 s0, 6, s0
	s_cselect_b32 s1, 0x400, s1
	s_cselect_b32 s2, 7, s2
	s_cselect_b32 s3, 0x400000, s3
	s_cselect_b32 s7, 0x2680000, s7
	s_cselect_b32 s11, 0x1d80, s11
	s_cmp_ge_u32 s52, 0x2180
	s_cselect_b32 s0, 6, s0
	s_cselect_b32 s1, 0x400, s1
	s_cselect_b32 s2, 7, s2
	s_cselect_b32 s3, 0x800000, s3
	s_cselect_b32 s7, 0x2a80000, s7
	s_cselect_b32 s11, 0x2180, s11
	s_lshl_b32 s15, s2, 3
	s_add_i32 s15, s15, 0x60
	s_load_dwordx2 s[18:19], s[54:55], s15
	s_sub_i32 s15, s52, s11
	s_lshl_b32 s2, 1, s0
	s_add_i32 s2, s2, -1
	s_and_b32 s2, s15, s2
	s_lshl_b32 s2, s2, 6
	s_lshr_b32 s15, s15, s0
	s_lshl_b32 s15, s15, 6
	s_mov_b32 s6, s0
	s_add_i32 s11, s0, 6
	s_lshl_b32 s11, s15, s11
	s_add_i32 s11, s11, s7
	s_add_i32 s11, s11, s2
	s_lshl_b32 s11, s11, 1
	s_add_u32 s4, s78, s11
	s_addc_u32 s5, s79, 0
	s_mul_i32 s7, s2, s1
	s_add_i32 s7, s7, s3
	s_add_i32 s7, s7, s15
	s_lshl_b32 s7, s7, 2
	s_lshl_b32 s3, s1, 6
	v_mul_u32_u24_e32 v81, s1, v74
	v_add_u32_e32 v81, v81, v75
	v_lshlrev_b32_e32 v80, 2, v81
	v_add_u32_e32 v81, s15, v75
	v_mov_b32_e32 v2, 0
	v_mov_b32_e32 v3, 0
	v_mov_b32_e32 v4, 0
	v_mov_b32_e32 v5, 0
	v_mov_b32_e32 v6, 0
	v_mov_b32_e32 v7, 0
	v_mov_b32_e32 v8, 0
	v_mov_b32_e32 v9, 0
	v_mov_b32_e32 v10, 0
	v_mov_b32_e32 v11, 0
	v_mov_b32_e32 v12, 0
	v_mov_b32_e32 v13, 0
	v_mov_b32_e32 v14, 0
	v_mov_b32_e32 v15, 0
	v_mov_b32_e32 v16, 0
	v_mov_b32_e32 v17, 0
	s_waitcnt lgkmcnt(0)
	s_add_u32 s18, s18, s7
	s_addc_u32 s19, s19, 0
	v_cmp_gt_u32_e32 vcc, s1, v81
	s_and_saveexec_b64 s[100:101], vcc
	global_load_dwordx4 v[2:5], v80, s[18:19]
	s_add_u32 s18, s18, s3
	s_addc_u32 s19, s19, 0
	global_load_dwordx4 v[6:9], v80, s[18:19]
	s_add_u32 s18, s18, s3
	s_addc_u32 s19, s19, 0
	global_load_dwordx4 v[10:13], v80, s[18:19]
	s_add_u32 s18, s18, s3
	s_addc_u32 s19, s19, 0
	global_load_dwordx4 v[14:17], v80, s[18:19]
	s_mov_b64 exec, s[100:101]
	s_waitcnt vmcnt(0)
	ds_write_b32 v76, v2
	ds_write_b32 v76, v3 offset:4
	ds_write_b32 v76, v4 offset:8
	ds_write_b32 v76, v5 offset:12
	ds_write_b32 v76, v6 offset:4160
	ds_write_b32 v76, v7 offset:4164
	ds_write_b32 v76, v8 offset:4168
	ds_write_b32 v76, v9 offset:4172
	ds_write_b32 v76, v10 offset:8320
	ds_write_b32 v76, v11 offset:8324
	ds_write_b32 v76, v12 offset:8328
	ds_write_b32 v76, v13 offset:8332
	ds_write_b32 v76, v14 offset:12480
	ds_write_b32 v76, v15 offset:12484
	ds_write_b32 v76, v16 offset:12488
	ds_write_b32 v76, v17 offset:12492
	s_waitcnt lgkmcnt(0)
	s_barrier
	ds_read_b32 v50, v77
	ds_read_b32 v51, v77 offset:260
	ds_read_b32 v52, v77 offset:520
	ds_read_b32 v53, v77 offset:780
	ds_read_b32 v54, v77 offset:1040
	ds_read_b32 v55, v77 offset:1300
	ds_read_b32 v56, v77 offset:1560
	ds_read_b32 v57, v77 offset:1820
	ds_read_b32 v58, v77 offset:2080
	ds_read_b32 v59, v77 offset:2340
	ds_read_b32 v60, v77 offset:2600
	ds_read_b32 v61, v77 offset:2860
	ds_read_b32 v62, v77 offset:3120
	ds_read_b32 v63, v77 offset:3380
	ds_read_b32 v64, v77 offset:3640
	ds_read_b32 v65, v77 offset:3900
	s_add_i32 s15, s6, 7
	v_lshlrev_b32_e32 v82, s15, v78
	v_add_u32_e32 v82, v82, v79
	s_waitcnt lgkmcnt(0)
	v_cvt_pk_bf16_f32 v66, v50, v51
	v_cvt_pk_bf16_f32 v67, v52, v53
	v_cvt_pk_bf16_f32 v68, v54, v55
	v_cvt_pk_bf16_f32 v69, v56, v57
	v_cvt_pk_bf16_f32 v70, v58, v59
	v_cvt_pk_bf16_f32 v71, v60, v61
	v_cvt_pk_bf16_f32 v72, v62, v63
	v_cvt_pk_bf16_f32 v73, v64, v65
	global_store_dwordx4 v82, v[66:69], s[4:5]
	global_store_dwordx4 v82, v[70:73], s[4:5] offset:16
	s_barrier
	s_add_i32 s34, s34, 1
	s_mul_i32 s15, s34, s35
	s_cmp_lt_u32 s15, 0x2580
	s_cbranch_scc1 .Lcvta_loop
	s_waitcnt vmcnt(0)
	s_branch .LBB0_842
